# hdn phases: 15 of the 32 x-row loads issued together with the modulation loads (before the modp wait) instead of after it
# speedup vs baseline: 1.0031x; 1.0031x over previous
.Lmy_hdn0_loop:
	s_lshr_b32 s5, s4, 7
	s_mul_i32 s5, s5, 0x3000
	s_add_u32 s6, s50, s5
	s_addc_u32 s7, s51, 0
	s_add_u32 s6, s6, 0x10c0000
	s_addc_u32 s7, s7, 0
	v_add_u32_e32 v210, 0x1000, v129
	s_barrier
	global_load_dwordx4 v[0:3], v129, s[6:7]
	global_load_dwordx4 v[32:35], v210, s[6:7]
	s_add_u32 s6, s6, 0xc000
	s_addc_u32 s7, s7, 0
	global_load_dwordx4 v[4:7], v129, s[6:7]
	global_load_dwordx4 v[36:39], v210, s[6:7]
	s_add_u32 s6, s6, 0xc000
	s_addc_u32 s7, s7, 0
	global_load_dwordx4 v[8:11], v129, s[6:7]
	global_load_dwordx4 v[40:43], v210, s[6:7]
	s_add_u32 s6, s6, 0xc000
	s_addc_u32 s7, s7, 0
	global_load_dwordx4 v[12:15], v129, s[6:7]
	global_load_dwordx4 v[44:47], v210, s[6:7]
	s_add_u32 s6, s6, 0xc000
	s_addc_u32 s7, s7, 0
	global_load_dwordx4 v[16:19], v129, s[6:7]
	global_load_dwordx4 v[48:51], v210, s[6:7]
	s_add_u32 s6, s6, 0xc000
	s_addc_u32 s7, s7, 0
	global_load_dwordx4 v[20:23], v129, s[6:7]
	global_load_dwordx4 v[52:55], v210, s[6:7]
	s_add_u32 s6, s6, 0xc000
	s_addc_u32 s7, s7, 0
	global_load_dwordx4 v[24:27], v129, s[6:7]
	global_load_dwordx4 v[56:59], v210, s[6:7]
	s_add_u32 s6, s6, 0xc000
	s_addc_u32 s7, s7, 0
	global_load_dwordx4 v[28:31], v129, s[6:7]
	global_load_dwordx4 v[60:63], v210, s[6:7]
	global_load_dwordx4 v[64:67], v129, s[74:75]
	v_and_b32_e32 v173, 63, v131
	v_lshrrev_b32_e32 v172, 6, v131
	v_lshlrev_b32_e32 v168, 4, v173
	v_lshl_add_u32 v168, v172, 15, v168
	v_lshrrev_b32_e32 v169, 3, v173
	v_lshlrev_b32_e32 v169, 10, v169
	v_bfe_u32 v170, v173, 1, 2
	v_lshl_or_b32 v169, v170, 8, v169
	v_and_b32_e32 v170, 1, v173
	v_lshl_or_b32 v169, v170, 3, v169
	v_lshrrev_b32_e32 v170, 1, v172
	v_lshl_or_b32 v169, v170, 15, v169
	v_and_b32_e32 v170, 1, v172
	v_lshl_or_b32 v169, v170, 7, v169
	v_add_u32_e32 v170, 0x2000, v169
	v_add_u32_e32 v171, 0x4000, v169
	v_add_u32_e32 v172, 0x6000, v169
	v_lshlrev_b32_e32 v173, 4, v173
	v_mov_b32_e32 v174, 0x3a800000
	s_lshl_b32 s5, s4, 17
	s_add_u32 s8, s68, s5
	s_addc_u32 s9, s69, 0
	s_lshl_b32 s5, s4, 16
	s_add_u32 s10, s50, s5
	s_addc_u32 s11, s51, 0
	s_add_u32 s10, s10, 0x3a00000
	s_addc_u32 s11, s11, 0
	s_add_u32 s12, s8, 0x4000
	s_addc_u32 s13, s9, 0
	global_load_dwordx4 v[68:71], v168, s[12:13] offset:1024 nt
	global_load_dwordx4 v[72:75], v168, s[12:13] offset:2048 nt
	global_load_dwordx4 v[76:79], v168, s[12:13] offset:3072 nt
	s_add_u32 s12, s12, 0x1000
	s_addc_u32 s13, s13, 0
	global_load_dwordx4 v[80:83], v168, s[12:13] offset:0 nt
	global_load_dwordx4 v[84:87], v168, s[12:13] offset:1024 nt
	global_load_dwordx4 v[88:91], v168, s[12:13] offset:2048 nt
	global_load_dwordx4 v[92:95], v168, s[12:13] offset:3072 nt
	s_add_u32 s12, s12, 0x1000
	s_addc_u32 s13, s13, 0
	global_load_dwordx4 v[96:99], v168, s[12:13] offset:0 nt
	global_load_dwordx4 v[100:103], v168, s[12:13] offset:1024 nt
	global_load_dwordx4 v[104:107], v168, s[12:13] offset:2048 nt
	global_load_dwordx4 v[108:111], v168, s[12:13] offset:3072 nt
	s_add_u32 s12, s12, 0x1000
	s_addc_u32 s13, s13, 0
	global_load_dwordx4 v[112:115], v168, s[12:13] offset:0 nt
	global_load_dwordx4 v[116:119], v168, s[12:13] offset:1024 nt
	global_load_dwordx4 v[120:123], v168, s[12:13] offset:2048 nt
	global_load_dwordx4 v[124:127], v168, s[12:13] offset:3072 nt
	s_waitcnt vmcnt(15)
	v_add_f32_e32 v0, v0, v4
	v_add_f32_e32 v0, v0, v8
	v_add_f32_e32 v0, v0, v12
	v_add_f32_e32 v0, v0, v16
	v_add_f32_e32 v0, v0, v20
	v_add_f32_e32 v0, v0, v24
	v_add_f32_e32 v0, v0, v28
	v_add_f32_e32 v1, v1, v5
	v_add_f32_e32 v1, v1, v9
	v_add_f32_e32 v1, v1, v13
	v_add_f32_e32 v1, v1, v17
	v_add_f32_e32 v1, v1, v21
	v_add_f32_e32 v1, v1, v25
	v_add_f32_e32 v1, v1, v29
	v_add_f32_e32 v2, v2, v6
	v_add_f32_e32 v2, v2, v10
	v_add_f32_e32 v2, v2, v14
	v_add_f32_e32 v2, v2, v18
	v_add_f32_e32 v2, v2, v22
	v_add_f32_e32 v2, v2, v26
	v_add_f32_e32 v2, v2, v30
	v_add_f32_e32 v3, v3, v7
	v_add_f32_e32 v3, v3, v11
	v_add_f32_e32 v3, v3, v15
	v_add_f32_e32 v3, v3, v19
	v_add_f32_e32 v3, v3, v23
	v_add_f32_e32 v3, v3, v27
	v_add_f32_e32 v3, v3, v31
	v_add_f32_e32 v32, v32, v36
	v_add_f32_e32 v32, v32, v40
	v_add_f32_e32 v32, v32, v44
	v_add_f32_e32 v32, v32, v48
	v_add_f32_e32 v32, v32, v52
	v_add_f32_e32 v32, v32, v56
	v_add_f32_e32 v32, v32, v60
	v_add_f32_e32 v33, v33, v37
	v_add_f32_e32 v33, v33, v41
	v_add_f32_e32 v33, v33, v45
	v_add_f32_e32 v33, v33, v49
	v_add_f32_e32 v33, v33, v53
	v_add_f32_e32 v33, v33, v57
	v_add_f32_e32 v33, v33, v61
	v_add_f32_e32 v34, v34, v38
	v_add_f32_e32 v34, v34, v42
	v_add_f32_e32 v34, v34, v46
	v_add_f32_e32 v34, v34, v50
	v_add_f32_e32 v34, v34, v54
	v_add_f32_e32 v34, v34, v58
	v_add_f32_e32 v34, v34, v62
	v_add_f32_e32 v35, v35, v39
	v_add_f32_e32 v35, v35, v43
	v_add_f32_e32 v35, v35, v47
	v_add_f32_e32 v35, v35, v51
	v_add_f32_e32 v35, v35, v55
	v_add_f32_e32 v35, v35, v59
	v_add_f32_e32 v35, v35, v63
	v_add_f32_e32 v32, 1.0, v32
	v_add_f32_e32 v33, 1.0, v33
	v_add_f32_e32 v34, 1.0, v34
	v_add_f32_e32 v35, 1.0, v35
	v_mul_f32_e32 v200, v64, v32
	v_mul_f32_e32 v201, v65, v33
	v_mul_f32_e32 v202, v66, v34
	v_mul_f32_e32 v203, v67, v35
	v_mov_b32_e32 v204, v0
	v_mov_b32_e32 v205, v1
	v_mov_b32_e32 v206, v2
	v_mov_b32_e32 v207, v3
	ds_write_b128 v129, v[200:203]
	ds_write_b128 v129, v[204:207] offset:4096
	global_load_dwordx4 v[0:3], v168, s[8:9] offset:0 nt
	global_load_dwordx4 v[4:7], v168, s[8:9] offset:1024 nt
	global_load_dwordx4 v[8:11], v168, s[8:9] offset:2048 nt
	global_load_dwordx4 v[12:15], v168, s[8:9] offset:3072 nt
	s_add_u32 s8, s8, 0x1000
	s_addc_u32 s9, s9, 0
	global_load_dwordx4 v[16:19], v168, s[8:9] offset:0 nt
	global_load_dwordx4 v[20:23], v168, s[8:9] offset:1024 nt
	global_load_dwordx4 v[24:27], v168, s[8:9] offset:2048 nt
	global_load_dwordx4 v[28:31], v168, s[8:9] offset:3072 nt
	s_add_u32 s8, s8, 0x1000
	s_addc_u32 s9, s9, 0
	global_load_dwordx4 v[32:35], v168, s[8:9] offset:0 nt
	global_load_dwordx4 v[36:39], v168, s[8:9] offset:1024 nt
	global_load_dwordx4 v[40:43], v168, s[8:9] offset:2048 nt
	global_load_dwordx4 v[44:47], v168, s[8:9] offset:3072 nt
	s_add_u32 s8, s8, 0x1000
	s_addc_u32 s9, s9, 0
	global_load_dwordx4 v[48:51], v168, s[8:9] offset:0 nt
	global_load_dwordx4 v[52:55], v168, s[8:9] offset:1024 nt
	global_load_dwordx4 v[56:59], v168, s[8:9] offset:2048 nt
	global_load_dwordx4 v[60:63], v168, s[8:9] offset:3072 nt
	s_add_u32 s8, s8, 0x1000
	s_addc_u32 s9, s9, 0
	global_load_dwordx4 v[64:67], v168, s[8:9] offset:0 nt
	s_waitcnt lgkmcnt(0)
	s_barrier
	ds_read_b128 v[178:181], v173 offset:0
	ds_read_b128 v[194:197], v173 offset:4096
	ds_read_b128 v[182:185], v173 offset:1024
	ds_read_b128 v[198:201], v173 offset:5120
	ds_read_b128 v[186:189], v173 offset:2048
	ds_read_b128 v[202:205], v173 offset:6144
	ds_read_b128 v[190:193], v173 offset:3072
	ds_read_b128 v[206:209], v173 offset:7168
	s_waitcnt vmcnt(25)
	v_mul_f32_e32 v165, v80, v80
	v_fmac_f32_e32 v165, v81, v81
	v_fmac_f32_e32 v165, v82, v82
	v_fmac_f32_e32 v165, v83, v83
	v_fmac_f32_e32 v165, v84, v84
	v_fmac_f32_e32 v165, v85, v85
	v_fmac_f32_e32 v165, v86, v86
	v_fmac_f32_e32 v165, v87, v87
	v_fmac_f32_e32 v165, v88, v88
	v_fmac_f32_e32 v165, v89, v89
	v_fmac_f32_e32 v165, v90, v90
	v_fmac_f32_e32 v165, v91, v91
	v_fmac_f32_e32 v165, v92, v92
	v_fmac_f32_e32 v165, v93, v93
	v_fmac_f32_e32 v165, v94, v94
	v_fmac_f32_e32 v165, v95, v95
	s_waitcnt vmcnt(21)
	v_mul_f32_e32 v166, v96, v96
	v_fmac_f32_e32 v166, v97, v97
	v_fmac_f32_e32 v166, v98, v98
	v_fmac_f32_e32 v166, v99, v99
	v_fmac_f32_e32 v166, v100, v100
	v_fmac_f32_e32 v166, v101, v101
	v_fmac_f32_e32 v166, v102, v102
	v_fmac_f32_e32 v166, v103, v103
	v_fmac_f32_e32 v166, v104, v104
	v_fmac_f32_e32 v166, v105, v105
	v_fmac_f32_e32 v166, v106, v106
	v_fmac_f32_e32 v166, v107, v107
	v_fmac_f32_e32 v166, v108, v108
	v_fmac_f32_e32 v166, v109, v109
	v_fmac_f32_e32 v166, v110, v110
	v_fmac_f32_e32 v166, v111, v111
	s_waitcnt vmcnt(17)
	v_mul_f32_e32 v167, v112, v112
	v_fmac_f32_e32 v167, v113, v113
	v_fmac_f32_e32 v167, v114, v114
	v_fmac_f32_e32 v167, v115, v115
	v_fmac_f32_e32 v167, v116, v116
	v_fmac_f32_e32 v167, v117, v117
	v_fmac_f32_e32 v167, v118, v118
	v_fmac_f32_e32 v167, v119, v119
	v_fmac_f32_e32 v167, v120, v120
	v_fmac_f32_e32 v167, v121, v121
	v_fmac_f32_e32 v167, v122, v122
	v_fmac_f32_e32 v167, v123, v123
	v_fmac_f32_e32 v167, v124, v124
	v_fmac_f32_e32 v167, v125, v125
	v_fmac_f32_e32 v167, v126, v126
	v_fmac_f32_e32 v167, v127, v127
	s_waitcnt vmcnt(13)
	v_mul_f32_e32 v160, v0, v0
	v_fmac_f32_e32 v160, v1, v1
	v_fmac_f32_e32 v160, v2, v2
	v_fmac_f32_e32 v160, v3, v3
	v_fmac_f32_e32 v160, v4, v4
	v_fmac_f32_e32 v160, v5, v5
	v_fmac_f32_e32 v160, v6, v6
	v_fmac_f32_e32 v160, v7, v7
	v_fmac_f32_e32 v160, v8, v8
	v_fmac_f32_e32 v160, v9, v9
	v_fmac_f32_e32 v160, v10, v10
	v_fmac_f32_e32 v160, v11, v11
	v_fmac_f32_e32 v160, v12, v12
	v_fmac_f32_e32 v160, v13, v13
	v_fmac_f32_e32 v160, v14, v14
	v_fmac_f32_e32 v160, v15, v15
	s_waitcnt vmcnt(9)
	v_mul_f32_e32 v161, v16, v16
	v_fmac_f32_e32 v161, v17, v17
	v_fmac_f32_e32 v161, v18, v18
	v_fmac_f32_e32 v161, v19, v19
	v_fmac_f32_e32 v161, v20, v20
	v_fmac_f32_e32 v161, v21, v21
	v_fmac_f32_e32 v161, v22, v22
	v_fmac_f32_e32 v161, v23, v23
	v_fmac_f32_e32 v161, v24, v24
	v_fmac_f32_e32 v161, v25, v25
	v_fmac_f32_e32 v161, v26, v26
	v_fmac_f32_e32 v161, v27, v27
	v_fmac_f32_e32 v161, v28, v28
	v_fmac_f32_e32 v161, v29, v29
	v_fmac_f32_e32 v161, v30, v30
	v_fmac_f32_e32 v161, v31, v31
	s_waitcnt vmcnt(5)
	v_mul_f32_e32 v162, v32, v32
	v_fmac_f32_e32 v162, v33, v33
	v_fmac_f32_e32 v162, v34, v34
	v_fmac_f32_e32 v162, v35, v35
	v_fmac_f32_e32 v162, v36, v36
	v_fmac_f32_e32 v162, v37, v37
	v_fmac_f32_e32 v162, v38, v38
	v_fmac_f32_e32 v162, v39, v39
	v_fmac_f32_e32 v162, v40, v40
	v_fmac_f32_e32 v162, v41, v41
	v_fmac_f32_e32 v162, v42, v42
	v_fmac_f32_e32 v162, v43, v43
	v_fmac_f32_e32 v162, v44, v44
	v_fmac_f32_e32 v162, v45, v45
	v_fmac_f32_e32 v162, v46, v46
	v_fmac_f32_e32 v162, v47, v47
	s_waitcnt vmcnt(1)
	v_mul_f32_e32 v163, v48, v48
	v_fmac_f32_e32 v163, v49, v49
	v_fmac_f32_e32 v163, v50, v50
	v_fmac_f32_e32 v163, v51, v51
	v_fmac_f32_e32 v163, v52, v52
	v_fmac_f32_e32 v163, v53, v53
	v_fmac_f32_e32 v163, v54, v54
	v_fmac_f32_e32 v163, v55, v55
	v_fmac_f32_e32 v163, v56, v56
	v_fmac_f32_e32 v163, v57, v57
	v_fmac_f32_e32 v163, v58, v58
	v_fmac_f32_e32 v163, v59, v59
	v_fmac_f32_e32 v163, v60, v60
	v_fmac_f32_e32 v163, v61, v61
	v_fmac_f32_e32 v163, v62, v62
	v_fmac_f32_e32 v163, v63, v63
	s_waitcnt vmcnt(0)
	v_mul_f32_e32 v164, v64, v64
	v_fmac_f32_e32 v164, v65, v65
	v_fmac_f32_e32 v164, v66, v66
	v_fmac_f32_e32 v164, v67, v67
	v_fmac_f32_e32 v164, v68, v68
	v_fmac_f32_e32 v164, v69, v69
	v_fmac_f32_e32 v164, v70, v70
	v_fmac_f32_e32 v164, v71, v71
	v_fmac_f32_e32 v164, v72, v72
	v_fmac_f32_e32 v164, v73, v73
	v_fmac_f32_e32 v164, v74, v74
	v_fmac_f32_e32 v164, v75, v75
	v_fmac_f32_e32 v164, v76, v76
	v_fmac_f32_e32 v164, v77, v77
	v_fmac_f32_e32 v164, v78, v78
	v_fmac_f32_e32 v164, v79, v79
	v_add_f32_dpp v160, v160, v160 quad_perm:[1,0,3,2] row_mask:0xf bank_mask:0xf
	v_add_f32_dpp v161, v161, v161 quad_perm:[1,0,3,2] row_mask:0xf bank_mask:0xf
	v_add_f32_dpp v162, v162, v162 quad_perm:[1,0,3,2] row_mask:0xf bank_mask:0xf
	v_add_f32_dpp v163, v163, v163 quad_perm:[1,0,3,2] row_mask:0xf bank_mask:0xf
	v_add_f32_dpp v164, v164, v164 quad_perm:[1,0,3,2] row_mask:0xf bank_mask:0xf
	v_add_f32_dpp v165, v165, v165 quad_perm:[1,0,3,2] row_mask:0xf bank_mask:0xf
	v_add_f32_dpp v166, v166, v166 quad_perm:[1,0,3,2] row_mask:0xf bank_mask:0xf
	v_add_f32_dpp v167, v167, v167 quad_perm:[1,0,3,2] row_mask:0xf bank_mask:0xf
	v_add_f32_dpp v160, v160, v160 quad_perm:[2,3,0,1] row_mask:0xf bank_mask:0xf
	v_add_f32_dpp v161, v161, v161 quad_perm:[2,3,0,1] row_mask:0xf bank_mask:0xf
	v_add_f32_dpp v162, v162, v162 quad_perm:[2,3,0,1] row_mask:0xf bank_mask:0xf
	v_add_f32_dpp v163, v163, v163 quad_perm:[2,3,0,1] row_mask:0xf bank_mask:0xf
	v_add_f32_dpp v164, v164, v164 quad_perm:[2,3,0,1] row_mask:0xf bank_mask:0xf
	v_add_f32_dpp v165, v165, v165 quad_perm:[2,3,0,1] row_mask:0xf bank_mask:0xf
	v_add_f32_dpp v166, v166, v166 quad_perm:[2,3,0,1] row_mask:0xf bank_mask:0xf
	v_add_f32_dpp v167, v167, v167 quad_perm:[2,3,0,1] row_mask:0xf bank_mask:0xf
	v_add_f32_dpp v160, v160, v160 row_half_mirror row_mask:0xf bank_mask:0xf
	v_add_f32_dpp v161, v161, v161 row_half_mirror row_mask:0xf bank_mask:0xf
	v_add_f32_dpp v162, v162, v162 row_half_mirror row_mask:0xf bank_mask:0xf
	v_add_f32_dpp v163, v163, v163 row_half_mirror row_mask:0xf bank_mask:0xf
	v_add_f32_dpp v164, v164, v164 row_half_mirror row_mask:0xf bank_mask:0xf
	v_add_f32_dpp v165, v165, v165 row_half_mirror row_mask:0xf bank_mask:0xf
	v_add_f32_dpp v166, v166, v166 row_half_mirror row_mask:0xf bank_mask:0xf
	v_add_f32_dpp v167, v167, v167 row_half_mirror row_mask:0xf bank_mask:0xf
	v_add_f32_dpp v160, v160, v160 row_mirror row_mask:0xf bank_mask:0xf
	v_add_f32_dpp v161, v161, v161 row_mirror row_mask:0xf bank_mask:0xf
	v_add_f32_dpp v162, v162, v162 row_mirror row_mask:0xf bank_mask:0xf
	v_add_f32_dpp v163, v163, v163 row_mirror row_mask:0xf bank_mask:0xf
	v_add_f32_dpp v164, v164, v164 row_mirror row_mask:0xf bank_mask:0xf
	v_add_f32_dpp v165, v165, v165 row_mirror row_mask:0xf bank_mask:0xf
	v_add_f32_dpp v166, v166, v166 row_mirror row_mask:0xf bank_mask:0xf
	v_add_f32_dpp v167, v167, v167 row_mirror row_mask:0xf bank_mask:0xf
	v_add_f32_dpp v160, v160, v160 row_bcast:15 row_mask:0xa bank_mask:0xf
	v_add_f32_dpp v161, v161, v161 row_bcast:15 row_mask:0xa bank_mask:0xf
	v_add_f32_dpp v162, v162, v162 row_bcast:15 row_mask:0xa bank_mask:0xf
	v_add_f32_dpp v163, v163, v163 row_bcast:15 row_mask:0xa bank_mask:0xf
	v_add_f32_dpp v164, v164, v164 row_bcast:15 row_mask:0xa bank_mask:0xf
	v_add_f32_dpp v165, v165, v165 row_bcast:15 row_mask:0xa bank_mask:0xf
	v_add_f32_dpp v166, v166, v166 row_bcast:15 row_mask:0xa bank_mask:0xf
	v_add_f32_dpp v167, v167, v167 row_bcast:15 row_mask:0xa bank_mask:0xf
	v_add_f32_dpp v160, v160, v160 row_bcast:31 row_mask:0xc bank_mask:0xf
	v_add_f32_dpp v161, v161, v161 row_bcast:31 row_mask:0xc bank_mask:0xf
	v_add_f32_dpp v162, v162, v162 row_bcast:31 row_mask:0xc bank_mask:0xf
	v_add_f32_dpp v163, v163, v163 row_bcast:31 row_mask:0xc bank_mask:0xf
	v_add_f32_dpp v164, v164, v164 row_bcast:31 row_mask:0xc bank_mask:0xf
	v_add_f32_dpp v165, v165, v165 row_bcast:31 row_mask:0xc bank_mask:0xf
	v_add_f32_dpp v166, v166, v166 row_bcast:31 row_mask:0xc bank_mask:0xf
	v_add_f32_dpp v167, v167, v167 row_bcast:31 row_mask:0xc bank_mask:0xf
	v_fmaak_f32 v160, v160, v174, 0x358637bd
	v_fmaak_f32 v161, v161, v174, 0x358637bd
	v_fmaak_f32 v162, v162, v174, 0x358637bd
	v_fmaak_f32 v163, v163, v174, 0x358637bd
	v_fmaak_f32 v164, v164, v174, 0x358637bd
	v_fmaak_f32 v165, v165, v174, 0x358637bd
	v_fmaak_f32 v166, v166, v174, 0x358637bd
	v_fmaak_f32 v167, v167, v174, 0x358637bd
	v_rsq_f32_e32 v160, v160
	v_rsq_f32_e32 v161, v161
	v_rsq_f32_e32 v162, v162
	v_rsq_f32_e32 v163, v163
	v_rsq_f32_e32 v164, v164
	v_rsq_f32_e32 v165, v165
	v_rsq_f32_e32 v166, v166
	v_rsq_f32_e32 v167, v167
	v_readlane_b32 s84, v160, 63
	v_readlane_b32 s85, v161, 63
	v_readlane_b32 s86, v162, 63
	v_readlane_b32 s87, v163, 63
	v_readlane_b32 s88, v164, 63
	v_readlane_b32 s89, v165, 63
	v_readlane_b32 s90, v166, 63
	v_readlane_b32 s91, v167, 63
	s_waitcnt lgkmcnt(0)
	v_mul_f32_e32 v0, s84, v0
	v_mul_f32_e32 v1, s84, v1
	v_mul_f32_e32 v2, s84, v2
	v_mul_f32_e32 v3, s84, v3
	v_fma_f32 v0, v0, v178, v194
	v_fma_f32 v1, v1, v179, v195
	v_fma_f32 v2, v2, v180, v196
	v_fma_f32 v3, v3, v181, v197
	v_cvt_pk_bf16_f32 v0, v0, v1
	v_cvt_pk_bf16_f32 v1, v2, v3
	global_store_dwordx2 v169, v[0:1], s[10:11] offset:0
	v_mul_f32_e32 v4, s84, v4
	v_mul_f32_e32 v5, s84, v5
	v_mul_f32_e32 v6, s84, v6
	v_mul_f32_e32 v7, s84, v7
	v_fma_f32 v4, v4, v182, v198
	v_fma_f32 v5, v5, v183, v199
	v_fma_f32 v6, v6, v184, v200
	v_fma_f32 v7, v7, v185, v201
	v_cvt_pk_bf16_f32 v4, v4, v5
	v_cvt_pk_bf16_f32 v5, v6, v7
	global_store_dwordx2 v170, v[4:5], s[10:11] offset:0
	v_mul_f32_e32 v8, s84, v8
	v_mul_f32_e32 v9, s84, v9
	v_mul_f32_e32 v10, s84, v10
	v_mul_f32_e32 v11, s84, v11
	v_fma_f32 v8, v8, v186, v202
	v_fma_f32 v9, v9, v187, v203
	v_fma_f32 v10, v10, v188, v204
	v_fma_f32 v11, v11, v189, v205
	v_cvt_pk_bf16_f32 v8, v8, v9
	v_cvt_pk_bf16_f32 v9, v10, v11
	global_store_dwordx2 v171, v[8:9], s[10:11] offset:0
	v_mul_f32_e32 v12, s84, v12
	v_mul_f32_e32 v13, s84, v13
	v_mul_f32_e32 v14, s84, v14
	v_mul_f32_e32 v15, s84, v15
	v_fma_f32 v12, v12, v190, v206
	v_fma_f32 v13, v13, v191, v207
	v_fma_f32 v14, v14, v192, v208
	v_fma_f32 v15, v15, v193, v209
	v_cvt_pk_bf16_f32 v12, v12, v13
	v_cvt_pk_bf16_f32 v13, v14, v15
	global_store_dwordx2 v172, v[12:13], s[10:11] offset:0
	v_mul_f32_e32 v16, s85, v16
	v_mul_f32_e32 v17, s85, v17
	v_mul_f32_e32 v18, s85, v18
	v_mul_f32_e32 v19, s85, v19
	v_fma_f32 v16, v16, v178, v194
	v_fma_f32 v17, v17, v179, v195
	v_fma_f32 v18, v18, v180, v196
	v_fma_f32 v19, v19, v181, v197
	v_cvt_pk_bf16_f32 v16, v16, v17
	v_cvt_pk_bf16_f32 v17, v18, v19
	global_store_dwordx2 v169, v[16:17], s[10:11] offset:16
	v_mul_f32_e32 v20, s85, v20
	v_mul_f32_e32 v21, s85, v21
	v_mul_f32_e32 v22, s85, v22
	v_mul_f32_e32 v23, s85, v23
	v_fma_f32 v20, v20, v182, v198
	v_fma_f32 v21, v21, v183, v199
	v_fma_f32 v22, v22, v184, v200
	v_fma_f32 v23, v23, v185, v201
	v_cvt_pk_bf16_f32 v20, v20, v21
	v_cvt_pk_bf16_f32 v21, v22, v23
	global_store_dwordx2 v170, v[20:21], s[10:11] offset:16
	v_mul_f32_e32 v24, s85, v24
	v_mul_f32_e32 v25, s85, v25
	v_mul_f32_e32 v26, s85, v26
	v_mul_f32_e32 v27, s85, v27
	v_fma_f32 v24, v24, v186, v202
	v_fma_f32 v25, v25, v187, v203
	v_fma_f32 v26, v26, v188, v204
	v_fma_f32 v27, v27, v189, v205
	v_cvt_pk_bf16_f32 v24, v24, v25
	v_cvt_pk_bf16_f32 v25, v26, v27
	global_store_dwordx2 v171, v[24:25], s[10:11] offset:16
	v_mul_f32_e32 v28, s85, v28
	v_mul_f32_e32 v29, s85, v29
	v_mul_f32_e32 v30, s85, v30
	v_mul_f32_e32 v31, s85, v31
	v_fma_f32 v28, v28, v190, v206
	v_fma_f32 v29, v29, v191, v207
	v_fma_f32 v30, v30, v192, v208
	v_fma_f32 v31, v31, v193, v209
	v_cvt_pk_bf16_f32 v28, v28, v29
	v_cvt_pk_bf16_f32 v29, v30, v31
	global_store_dwordx2 v172, v[28:29], s[10:11] offset:16
	v_mul_f32_e32 v32, s86, v32
	v_mul_f32_e32 v33, s86, v33
	v_mul_f32_e32 v34, s86, v34
	v_mul_f32_e32 v35, s86, v35
	v_fma_f32 v32, v32, v178, v194
	v_fma_f32 v33, v33, v179, v195
	v_fma_f32 v34, v34, v180, v196
	v_fma_f32 v35, v35, v181, v197
	v_cvt_pk_bf16_f32 v32, v32, v33
	v_cvt_pk_bf16_f32 v33, v34, v35
	global_store_dwordx2 v169, v[32:33], s[10:11] offset:32
	v_mul_f32_e32 v36, s86, v36
	v_mul_f32_e32 v37, s86, v37
	v_mul_f32_e32 v38, s86, v38
	v_mul_f32_e32 v39, s86, v39
	v_fma_f32 v36, v36, v182, v198
	v_fma_f32 v37, v37, v183, v199
	v_fma_f32 v38, v38, v184, v200
	v_fma_f32 v39, v39, v185, v201
	v_cvt_pk_bf16_f32 v36, v36, v37
	v_cvt_pk_bf16_f32 v37, v38, v39
	global_store_dwordx2 v170, v[36:37], s[10:11] offset:32
	v_mul_f32_e32 v40, s86, v40
	v_mul_f32_e32 v41, s86, v41
	v_mul_f32_e32 v42, s86, v42
	v_mul_f32_e32 v43, s86, v43
	v_fma_f32 v40, v40, v186, v202
	v_fma_f32 v41, v41, v187, v203
	v_fma_f32 v42, v42, v188, v204
	v_fma_f32 v43, v43, v189, v205
	v_cvt_pk_bf16_f32 v40, v40, v41
	v_cvt_pk_bf16_f32 v41, v42, v43
	global_store_dwordx2 v171, v[40:41], s[10:11] offset:32
	v_mul_f32_e32 v44, s86, v44
	v_mul_f32_e32 v45, s86, v45
	v_mul_f32_e32 v46, s86, v46
	v_mul_f32_e32 v47, s86, v47
	v_fma_f32 v44, v44, v190, v206
	v_fma_f32 v45, v45, v191, v207
	v_fma_f32 v46, v46, v192, v208
	v_fma_f32 v47, v47, v193, v209
	v_cvt_pk_bf16_f32 v44, v44, v45
	v_cvt_pk_bf16_f32 v45, v46, v47
	global_store_dwordx2 v172, v[44:45], s[10:11] offset:32
	v_mul_f32_e32 v48, s87, v48
	v_mul_f32_e32 v49, s87, v49
	v_mul_f32_e32 v50, s87, v50
	v_mul_f32_e32 v51, s87, v51
	v_fma_f32 v48, v48, v178, v194
	v_fma_f32 v49, v49, v179, v195
	v_fma_f32 v50, v50, v180, v196
	v_fma_f32 v51, v51, v181, v197
	v_cvt_pk_bf16_f32 v48, v48, v49
	v_cvt_pk_bf16_f32 v49, v50, v51
	global_store_dwordx2 v169, v[48:49], s[10:11] offset:48
	v_mul_f32_e32 v52, s87, v52
	v_mul_f32_e32 v53, s87, v53
	v_mul_f32_e32 v54, s87, v54
	v_mul_f32_e32 v55, s87, v55
	v_fma_f32 v52, v52, v182, v198
	v_fma_f32 v53, v53, v183, v199
	v_fma_f32 v54, v54, v184, v200
	v_fma_f32 v55, v55, v185, v201
	v_cvt_pk_bf16_f32 v52, v52, v53
	v_cvt_pk_bf16_f32 v53, v54, v55
	global_store_dwordx2 v170, v[52:53], s[10:11] offset:48
	v_mul_f32_e32 v56, s87, v56
	v_mul_f32_e32 v57, s87, v57
	v_mul_f32_e32 v58, s87, v58
	v_mul_f32_e32 v59, s87, v59
	v_fma_f32 v56, v56, v186, v202
	v_fma_f32 v57, v57, v187, v203
	v_fma_f32 v58, v58, v188, v204
	v_fma_f32 v59, v59, v189, v205
	v_cvt_pk_bf16_f32 v56, v56, v57
	v_cvt_pk_bf16_f32 v57, v58, v59
	global_store_dwordx2 v171, v[56:57], s[10:11] offset:48
	v_mul_f32_e32 v60, s87, v60
	v_mul_f32_e32 v61, s87, v61
	v_mul_f32_e32 v62, s87, v62
	v_mul_f32_e32 v63, s87, v63
	v_fma_f32 v60, v60, v190, v206
	v_fma_f32 v61, v61, v191, v207
	v_fma_f32 v62, v62, v192, v208
	v_fma_f32 v63, v63, v193, v209
	v_cvt_pk_bf16_f32 v60, v60, v61
	v_cvt_pk_bf16_f32 v61, v62, v63
	global_store_dwordx2 v172, v[60:61], s[10:11] offset:48
	v_mul_f32_e32 v64, s88, v64
	v_mul_f32_e32 v65, s88, v65
	v_mul_f32_e32 v66, s88, v66
	v_mul_f32_e32 v67, s88, v67
	v_fma_f32 v64, v64, v178, v194
	v_fma_f32 v65, v65, v179, v195
	v_fma_f32 v66, v66, v180, v196
	v_fma_f32 v67, v67, v181, v197
	v_cvt_pk_bf16_f32 v64, v64, v65
	v_cvt_pk_bf16_f32 v65, v66, v67
	global_store_dwordx2 v169, v[64:65], s[10:11] offset:64
	v_mul_f32_e32 v68, s88, v68
	v_mul_f32_e32 v69, s88, v69
	v_mul_f32_e32 v70, s88, v70
	v_mul_f32_e32 v71, s88, v71
	v_fma_f32 v68, v68, v182, v198
	v_fma_f32 v69, v69, v183, v199
	v_fma_f32 v70, v70, v184, v200
	v_fma_f32 v71, v71, v185, v201
	v_cvt_pk_bf16_f32 v68, v68, v69
	v_cvt_pk_bf16_f32 v69, v70, v71
	global_store_dwordx2 v170, v[68:69], s[10:11] offset:64
	v_mul_f32_e32 v72, s88, v72
	v_mul_f32_e32 v73, s88, v73
	v_mul_f32_e32 v74, s88, v74
	v_mul_f32_e32 v75, s88, v75
	v_fma_f32 v72, v72, v186, v202
	v_fma_f32 v73, v73, v187, v203
	v_fma_f32 v74, v74, v188, v204
	v_fma_f32 v75, v75, v189, v205
	v_cvt_pk_bf16_f32 v72, v72, v73
	v_cvt_pk_bf16_f32 v73, v74, v75
	global_store_dwordx2 v171, v[72:73], s[10:11] offset:64
	v_mul_f32_e32 v76, s88, v76
	v_mul_f32_e32 v77, s88, v77
	v_mul_f32_e32 v78, s88, v78
	v_mul_f32_e32 v79, s88, v79
	v_fma_f32 v76, v76, v190, v206
	v_fma_f32 v77, v77, v191, v207
	v_fma_f32 v78, v78, v192, v208
	v_fma_f32 v79, v79, v193, v209
	v_cvt_pk_bf16_f32 v76, v76, v77
	v_cvt_pk_bf16_f32 v77, v78, v79
	global_store_dwordx2 v172, v[76:77], s[10:11] offset:64
	v_mul_f32_e32 v80, s89, v80
	v_mul_f32_e32 v81, s89, v81
	v_mul_f32_e32 v82, s89, v82
	v_mul_f32_e32 v83, s89, v83
	v_fma_f32 v80, v80, v178, v194
	v_fma_f32 v81, v81, v179, v195
	v_fma_f32 v82, v82, v180, v196
	v_fma_f32 v83, v83, v181, v197
	v_cvt_pk_bf16_f32 v80, v80, v81
	v_cvt_pk_bf16_f32 v81, v82, v83
	global_store_dwordx2 v169, v[80:81], s[10:11] offset:80
	v_mul_f32_e32 v84, s89, v84
	v_mul_f32_e32 v85, s89, v85
	v_mul_f32_e32 v86, s89, v86
	v_mul_f32_e32 v87, s89, v87
	v_fma_f32 v84, v84, v182, v198
	v_fma_f32 v85, v85, v183, v199
	v_fma_f32 v86, v86, v184, v200
	v_fma_f32 v87, v87, v185, v201
	v_cvt_pk_bf16_f32 v84, v84, v85
	v_cvt_pk_bf16_f32 v85, v86, v87
	global_store_dwordx2 v170, v[84:85], s[10:11] offset:80
	v_mul_f32_e32 v88, s89, v88
	v_mul_f32_e32 v89, s89, v89
	v_mul_f32_e32 v90, s89, v90
	v_mul_f32_e32 v91, s89, v91
	v_fma_f32 v88, v88, v186, v202
	v_fma_f32 v89, v89, v187, v203
	v_fma_f32 v90, v90, v188, v204
	v_fma_f32 v91, v91, v189, v205
	v_cvt_pk_bf16_f32 v88, v88, v89
	v_cvt_pk_bf16_f32 v89, v90, v91
	global_store_dwordx2 v171, v[88:89], s[10:11] offset:80
	v_mul_f32_e32 v92, s89, v92
	v_mul_f32_e32 v93, s89, v93
	v_mul_f32_e32 v94, s89, v94
	v_mul_f32_e32 v95, s89, v95
	v_fma_f32 v92, v92, v190, v206
	v_fma_f32 v93, v93, v191, v207
	v_fma_f32 v94, v94, v192, v208
	v_fma_f32 v95, v95, v193, v209
	v_cvt_pk_bf16_f32 v92, v92, v93
	v_cvt_pk_bf16_f32 v93, v94, v95
	global_store_dwordx2 v172, v[92:93], s[10:11] offset:80
	v_mul_f32_e32 v96, s90, v96
	v_mul_f32_e32 v97, s90, v97
	v_mul_f32_e32 v98, s90, v98
	v_mul_f32_e32 v99, s90, v99
	v_fma_f32 v96, v96, v178, v194
	v_fma_f32 v97, v97, v179, v195
	v_fma_f32 v98, v98, v180, v196
	v_fma_f32 v99, v99, v181, v197
	v_cvt_pk_bf16_f32 v96, v96, v97
	v_cvt_pk_bf16_f32 v97, v98, v99
	global_store_dwordx2 v169, v[96:97], s[10:11] offset:96
	v_mul_f32_e32 v100, s90, v100
	v_mul_f32_e32 v101, s90, v101
	v_mul_f32_e32 v102, s90, v102
	v_mul_f32_e32 v103, s90, v103
	v_fma_f32 v100, v100, v182, v198
	v_fma_f32 v101, v101, v183, v199
	v_fma_f32 v102, v102, v184, v200
	v_fma_f32 v103, v103, v185, v201
	v_cvt_pk_bf16_f32 v100, v100, v101
	v_cvt_pk_bf16_f32 v101, v102, v103
	global_store_dwordx2 v170, v[100:101], s[10:11] offset:96
	v_mul_f32_e32 v104, s90, v104
	v_mul_f32_e32 v105, s90, v105
	v_mul_f32_e32 v106, s90, v106
	v_mul_f32_e32 v107, s90, v107
	v_fma_f32 v104, v104, v186, v202
	v_fma_f32 v105, v105, v187, v203
	v_fma_f32 v106, v106, v188, v204
	v_fma_f32 v107, v107, v189, v205
	v_cvt_pk_bf16_f32 v104, v104, v105
	v_cvt_pk_bf16_f32 v105, v106, v107
	global_store_dwordx2 v171, v[104:105], s[10:11] offset:96
	v_mul_f32_e32 v108, s90, v108
	v_mul_f32_e32 v109, s90, v109
	v_mul_f32_e32 v110, s90, v110
	v_mul_f32_e32 v111, s90, v111
	v_fma_f32 v108, v108, v190, v206
	v_fma_f32 v109, v109, v191, v207
	v_fma_f32 v110, v110, v192, v208
	v_fma_f32 v111, v111, v193, v209
	v_cvt_pk_bf16_f32 v108, v108, v109
	v_cvt_pk_bf16_f32 v109, v110, v111
	global_store_dwordx2 v172, v[108:109], s[10:11] offset:96
	v_mul_f32_e32 v112, s91, v112
	v_mul_f32_e32 v113, s91, v113
	v_mul_f32_e32 v114, s91, v114
	v_mul_f32_e32 v115, s91, v115
	v_fma_f32 v112, v112, v178, v194
	v_fma_f32 v113, v113, v179, v195
	v_fma_f32 v114, v114, v180, v196
	v_fma_f32 v115, v115, v181, v197
	v_cvt_pk_bf16_f32 v112, v112, v113
	v_cvt_pk_bf16_f32 v113, v114, v115
	global_store_dwordx2 v169, v[112:113], s[10:11] offset:112
	v_mul_f32_e32 v116, s91, v116
	v_mul_f32_e32 v117, s91, v117
	v_mul_f32_e32 v118, s91, v118
	v_mul_f32_e32 v119, s91, v119
	v_fma_f32 v116, v116, v182, v198
	v_fma_f32 v117, v117, v183, v199
	v_fma_f32 v118, v118, v184, v200
	v_fma_f32 v119, v119, v185, v201
	v_cvt_pk_bf16_f32 v116, v116, v117
	v_cvt_pk_bf16_f32 v117, v118, v119
	global_store_dwordx2 v170, v[116:117], s[10:11] offset:112
	v_mul_f32_e32 v120, s91, v120
	v_mul_f32_e32 v121, s91, v121
	v_mul_f32_e32 v122, s91, v122
	v_mul_f32_e32 v123, s91, v123
	v_fma_f32 v120, v120, v186, v202
	v_fma_f32 v121, v121, v187, v203
	v_fma_f32 v122, v122, v188, v204
	v_fma_f32 v123, v123, v189, v205
	v_cvt_pk_bf16_f32 v120, v120, v121
	v_cvt_pk_bf16_f32 v121, v122, v123
	global_store_dwordx2 v171, v[120:121], s[10:11] offset:112
	v_mul_f32_e32 v124, s91, v124
	v_mul_f32_e32 v125, s91, v125
	v_mul_f32_e32 v126, s91, v126
	v_mul_f32_e32 v127, s91, v127
	v_fma_f32 v124, v124, v190, v206
	v_fma_f32 v125, v125, v191, v207
	v_fma_f32 v126, v126, v192, v208
	v_fma_f32 v127, v127, v193, v209
	v_cvt_pk_bf16_f32 v124, v124, v125
	v_cvt_pk_bf16_f32 v125, v126, v127
	global_store_dwordx2 v172, v[124:125], s[10:11] offset:112
	s_add_i32 s4, s4, s3
	s_cmpk_lt_i32 s4, 0x200
	s_cbranch_scc1 .Lmy_hdn0_loop

.Lmy_hdn1_loop:
	s_lshr_b32 s5, s4, 7
	s_mul_i32 s5, s5, 0x3000
	s_add_u32 s6, s50, s5
	s_addc_u32 s7, s51, 0
	s_add_u32 s6, s6, 0x1120000
	s_addc_u32 s7, s7, 0
	v_add_u32_e32 v210, 0x1000, v129
	s_barrier
	global_load_dwordx4 v[0:3], v129, s[6:7]
	global_load_dwordx4 v[32:35], v210, s[6:7]
	s_add_u32 s6, s6, 0xc000
	s_addc_u32 s7, s7, 0
	global_load_dwordx4 v[4:7], v129, s[6:7]
	global_load_dwordx4 v[36:39], v210, s[6:7]
	s_add_u32 s6, s6, 0xc000
	s_addc_u32 s7, s7, 0
	global_load_dwordx4 v[8:11], v129, s[6:7]
	global_load_dwordx4 v[40:43], v210, s[6:7]
	s_add_u32 s6, s6, 0xc000
	s_addc_u32 s7, s7, 0
	global_load_dwordx4 v[12:15], v129, s[6:7]
	global_load_dwordx4 v[44:47], v210, s[6:7]
	s_add_u32 s6, s6, 0xc000
	s_addc_u32 s7, s7, 0
	global_load_dwordx4 v[16:19], v129, s[6:7]
	global_load_dwordx4 v[48:51], v210, s[6:7]
	s_add_u32 s6, s6, 0xc000
	s_addc_u32 s7, s7, 0
	global_load_dwordx4 v[20:23], v129, s[6:7]
	global_load_dwordx4 v[52:55], v210, s[6:7]
	s_add_u32 s6, s6, 0xc000
	s_addc_u32 s7, s7, 0
	global_load_dwordx4 v[24:27], v129, s[6:7]
	global_load_dwordx4 v[56:59], v210, s[6:7]
	s_add_u32 s6, s6, 0xc000
	s_addc_u32 s7, s7, 0
	global_load_dwordx4 v[28:31], v129, s[6:7]
	global_load_dwordx4 v[60:63], v210, s[6:7]
	global_load_dwordx4 v[64:67], v129, s[62:63]
	v_and_b32_e32 v173, 63, v131
	v_lshrrev_b32_e32 v172, 6, v131
	v_lshlrev_b32_e32 v168, 4, v173
	v_lshl_add_u32 v168, v172, 15, v168
	v_lshrrev_b32_e32 v169, 3, v173
	v_lshlrev_b32_e32 v169, 10, v169
	v_bfe_u32 v170, v173, 1, 2
	v_lshl_or_b32 v169, v170, 8, v169
	v_and_b32_e32 v170, 1, v173
	v_lshl_or_b32 v169, v170, 3, v169
	v_lshrrev_b32_e32 v170, 1, v172
	v_lshl_or_b32 v169, v170, 15, v169
	v_and_b32_e32 v170, 1, v172
	v_lshl_or_b32 v169, v170, 7, v169
	v_add_u32_e32 v170, 0x2000, v169
	v_add_u32_e32 v171, 0x4000, v169
	v_add_u32_e32 v172, 0x6000, v169
	v_lshlrev_b32_e32 v173, 4, v173
	v_mov_b32_e32 v174, 0x3a800000
	s_lshl_b32 s5, s4, 17
	s_add_u32 s8, s48, s5
	s_addc_u32 s9, s49, 0
	s_lshl_b32 s5, s4, 16
	s_add_u32 s10, s50, s5
	s_addc_u32 s11, s51, 0
	s_add_u32 s10, s10, 0x3a00000
	s_addc_u32 s11, s11, 0
	s_add_u32 s12, s8, 0x4000
	s_addc_u32 s13, s9, 0
	global_load_dwordx4 v[68:71], v168, s[12:13] offset:1024 nt
	global_load_dwordx4 v[72:75], v168, s[12:13] offset:2048 nt
	global_load_dwordx4 v[76:79], v168, s[12:13] offset:3072 nt
	s_add_u32 s12, s12, 0x1000
	s_addc_u32 s13, s13, 0
	global_load_dwordx4 v[80:83], v168, s[12:13] offset:0 nt
	global_load_dwordx4 v[84:87], v168, s[12:13] offset:1024 nt
	global_load_dwordx4 v[88:91], v168, s[12:13] offset:2048 nt
	global_load_dwordx4 v[92:95], v168, s[12:13] offset:3072 nt
	s_add_u32 s12, s12, 0x1000
	s_addc_u32 s13, s13, 0
	global_load_dwordx4 v[96:99], v168, s[12:13] offset:0 nt
	global_load_dwordx4 v[100:103], v168, s[12:13] offset:1024 nt
	global_load_dwordx4 v[104:107], v168, s[12:13] offset:2048 nt
	global_load_dwordx4 v[108:111], v168, s[12:13] offset:3072 nt
	s_add_u32 s12, s12, 0x1000
	s_addc_u32 s13, s13, 0
	global_load_dwordx4 v[112:115], v168, s[12:13] offset:0 nt
	global_load_dwordx4 v[116:119], v168, s[12:13] offset:1024 nt
	global_load_dwordx4 v[120:123], v168, s[12:13] offset:2048 nt
	global_load_dwordx4 v[124:127], v168, s[12:13] offset:3072 nt
	s_waitcnt vmcnt(15)
	v_add_f32_e32 v0, v0, v4
	v_add_f32_e32 v0, v0, v8
	v_add_f32_e32 v0, v0, v12
	v_add_f32_e32 v0, v0, v16
	v_add_f32_e32 v0, v0, v20
	v_add_f32_e32 v0, v0, v24
	v_add_f32_e32 v0, v0, v28
	v_add_f32_e32 v1, v1, v5
	v_add_f32_e32 v1, v1, v9
	v_add_f32_e32 v1, v1, v13
	v_add_f32_e32 v1, v1, v17
	v_add_f32_e32 v1, v1, v21
	v_add_f32_e32 v1, v1, v25
	v_add_f32_e32 v1, v1, v29
	v_add_f32_e32 v2, v2, v6
	v_add_f32_e32 v2, v2, v10
	v_add_f32_e32 v2, v2, v14
	v_add_f32_e32 v2, v2, v18
	v_add_f32_e32 v2, v2, v22
	v_add_f32_e32 v2, v2, v26
	v_add_f32_e32 v2, v2, v30
	v_add_f32_e32 v3, v3, v7
	v_add_f32_e32 v3, v3, v11
	v_add_f32_e32 v3, v3, v15
	v_add_f32_e32 v3, v3, v19
	v_add_f32_e32 v3, v3, v23
	v_add_f32_e32 v3, v3, v27
	v_add_f32_e32 v3, v3, v31
	v_add_f32_e32 v32, v32, v36
	v_add_f32_e32 v32, v32, v40
	v_add_f32_e32 v32, v32, v44
	v_add_f32_e32 v32, v32, v48
	v_add_f32_e32 v32, v32, v52
	v_add_f32_e32 v32, v32, v56
	v_add_f32_e32 v32, v32, v60
	v_add_f32_e32 v33, v33, v37
	v_add_f32_e32 v33, v33, v41
	v_add_f32_e32 v33, v33, v45
	v_add_f32_e32 v33, v33, v49
	v_add_f32_e32 v33, v33, v53
	v_add_f32_e32 v33, v33, v57
	v_add_f32_e32 v33, v33, v61
	v_add_f32_e32 v34, v34, v38
	v_add_f32_e32 v34, v34, v42
	v_add_f32_e32 v34, v34, v46
	v_add_f32_e32 v34, v34, v50
	v_add_f32_e32 v34, v34, v54
	v_add_f32_e32 v34, v34, v58
	v_add_f32_e32 v34, v34, v62
	v_add_f32_e32 v35, v35, v39
	v_add_f32_e32 v35, v35, v43
	v_add_f32_e32 v35, v35, v47
	v_add_f32_e32 v35, v35, v51
	v_add_f32_e32 v35, v35, v55
	v_add_f32_e32 v35, v35, v59
	v_add_f32_e32 v35, v35, v63
	v_add_f32_e32 v32, 1.0, v32
	v_add_f32_e32 v33, 1.0, v33
	v_add_f32_e32 v34, 1.0, v34
	v_add_f32_e32 v35, 1.0, v35
	v_mul_f32_e32 v200, v64, v32
	v_mul_f32_e32 v201, v65, v33
	v_mul_f32_e32 v202, v66, v34
	v_mul_f32_e32 v203, v67, v35
	v_mov_b32_e32 v204, v0
	v_mov_b32_e32 v205, v1
	v_mov_b32_e32 v206, v2
	v_mov_b32_e32 v207, v3
	ds_write_b128 v129, v[200:203]
	ds_write_b128 v129, v[204:207] offset:4096
	global_load_dwordx4 v[0:3], v168, s[8:9] offset:0 nt
	global_load_dwordx4 v[4:7], v168, s[8:9] offset:1024 nt
	global_load_dwordx4 v[8:11], v168, s[8:9] offset:2048 nt
	global_load_dwordx4 v[12:15], v168, s[8:9] offset:3072 nt
	s_add_u32 s8, s8, 0x1000
	s_addc_u32 s9, s9, 0
	global_load_dwordx4 v[16:19], v168, s[8:9] offset:0 nt
	global_load_dwordx4 v[20:23], v168, s[8:9] offset:1024 nt
	global_load_dwordx4 v[24:27], v168, s[8:9] offset:2048 nt
	global_load_dwordx4 v[28:31], v168, s[8:9] offset:3072 nt
	s_add_u32 s8, s8, 0x1000
	s_addc_u32 s9, s9, 0
	global_load_dwordx4 v[32:35], v168, s[8:9] offset:0 nt
	global_load_dwordx4 v[36:39], v168, s[8:9] offset:1024 nt
	global_load_dwordx4 v[40:43], v168, s[8:9] offset:2048 nt
	global_load_dwordx4 v[44:47], v168, s[8:9] offset:3072 nt
	s_add_u32 s8, s8, 0x1000
	s_addc_u32 s9, s9, 0
	global_load_dwordx4 v[48:51], v168, s[8:9] offset:0 nt
	global_load_dwordx4 v[52:55], v168, s[8:9] offset:1024 nt
	global_load_dwordx4 v[56:59], v168, s[8:9] offset:2048 nt
	global_load_dwordx4 v[60:63], v168, s[8:9] offset:3072 nt
	s_add_u32 s8, s8, 0x1000
	s_addc_u32 s9, s9, 0
	global_load_dwordx4 v[64:67], v168, s[8:9] offset:0 nt
	s_waitcnt lgkmcnt(0)
	s_barrier
	ds_read_b128 v[178:181], v173 offset:0
	ds_read_b128 v[194:197], v173 offset:4096
	ds_read_b128 v[182:185], v173 offset:1024
	ds_read_b128 v[198:201], v173 offset:5120
	ds_read_b128 v[186:189], v173 offset:2048
	ds_read_b128 v[202:205], v173 offset:6144
	ds_read_b128 v[190:193], v173 offset:3072
	ds_read_b128 v[206:209], v173 offset:7168
	s_waitcnt vmcnt(25)
	v_mul_f32_e32 v165, v80, v80
	v_fmac_f32_e32 v165, v81, v81
	v_fmac_f32_e32 v165, v82, v82
	v_fmac_f32_e32 v165, v83, v83
	v_fmac_f32_e32 v165, v84, v84
	v_fmac_f32_e32 v165, v85, v85
	v_fmac_f32_e32 v165, v86, v86
	v_fmac_f32_e32 v165, v87, v87
	v_fmac_f32_e32 v165, v88, v88
	v_fmac_f32_e32 v165, v89, v89
	v_fmac_f32_e32 v165, v90, v90
	v_fmac_f32_e32 v165, v91, v91
	v_fmac_f32_e32 v165, v92, v92
	v_fmac_f32_e32 v165, v93, v93
	v_fmac_f32_e32 v165, v94, v94
	v_fmac_f32_e32 v165, v95, v95
	s_waitcnt vmcnt(21)
	v_mul_f32_e32 v166, v96, v96
	v_fmac_f32_e32 v166, v97, v97
	v_fmac_f32_e32 v166, v98, v98
	v_fmac_f32_e32 v166, v99, v99
	v_fmac_f32_e32 v166, v100, v100
	v_fmac_f32_e32 v166, v101, v101
	v_fmac_f32_e32 v166, v102, v102
	v_fmac_f32_e32 v166, v103, v103
	v_fmac_f32_e32 v166, v104, v104
	v_fmac_f32_e32 v166, v105, v105
	v_fmac_f32_e32 v166, v106, v106
	v_fmac_f32_e32 v166, v107, v107
	v_fmac_f32_e32 v166, v108, v108
	v_fmac_f32_e32 v166, v109, v109
	v_fmac_f32_e32 v166, v110, v110
	v_fmac_f32_e32 v166, v111, v111
	s_waitcnt vmcnt(17)
	v_mul_f32_e32 v167, v112, v112
	v_fmac_f32_e32 v167, v113, v113
	v_fmac_f32_e32 v167, v114, v114
	v_fmac_f32_e32 v167, v115, v115
	v_fmac_f32_e32 v167, v116, v116
	v_fmac_f32_e32 v167, v117, v117
	v_fmac_f32_e32 v167, v118, v118
	v_fmac_f32_e32 v167, v119, v119
	v_fmac_f32_e32 v167, v120, v120
	v_fmac_f32_e32 v167, v121, v121
	v_fmac_f32_e32 v167, v122, v122
	v_fmac_f32_e32 v167, v123, v123
	v_fmac_f32_e32 v167, v124, v124
	v_fmac_f32_e32 v167, v125, v125
	v_fmac_f32_e32 v167, v126, v126
	v_fmac_f32_e32 v167, v127, v127
	s_waitcnt vmcnt(13)
	v_mul_f32_e32 v160, v0, v0
	v_fmac_f32_e32 v160, v1, v1
	v_fmac_f32_e32 v160, v2, v2
	v_fmac_f32_e32 v160, v3, v3
	v_fmac_f32_e32 v160, v4, v4
	v_fmac_f32_e32 v160, v5, v5
	v_fmac_f32_e32 v160, v6, v6
	v_fmac_f32_e32 v160, v7, v7
	v_fmac_f32_e32 v160, v8, v8
	v_fmac_f32_e32 v160, v9, v9
	v_fmac_f32_e32 v160, v10, v10
	v_fmac_f32_e32 v160, v11, v11
	v_fmac_f32_e32 v160, v12, v12
	v_fmac_f32_e32 v160, v13, v13
	v_fmac_f32_e32 v160, v14, v14
	v_fmac_f32_e32 v160, v15, v15
	s_waitcnt vmcnt(9)
	v_mul_f32_e32 v161, v16, v16
	v_fmac_f32_e32 v161, v17, v17
	v_fmac_f32_e32 v161, v18, v18
	v_fmac_f32_e32 v161, v19, v19
	v_fmac_f32_e32 v161, v20, v20
	v_fmac_f32_e32 v161, v21, v21
	v_fmac_f32_e32 v161, v22, v22
	v_fmac_f32_e32 v161, v23, v23
	v_fmac_f32_e32 v161, v24, v24
	v_fmac_f32_e32 v161, v25, v25
	v_fmac_f32_e32 v161, v26, v26
	v_fmac_f32_e32 v161, v27, v27
	v_fmac_f32_e32 v161, v28, v28
	v_fmac_f32_e32 v161, v29, v29
	v_fmac_f32_e32 v161, v30, v30
	v_fmac_f32_e32 v161, v31, v31
	s_waitcnt vmcnt(5)
	v_mul_f32_e32 v162, v32, v32
	v_fmac_f32_e32 v162, v33, v33
	v_fmac_f32_e32 v162, v34, v34
	v_fmac_f32_e32 v162, v35, v35
	v_fmac_f32_e32 v162, v36, v36
	v_fmac_f32_e32 v162, v37, v37
	v_fmac_f32_e32 v162, v38, v38
	v_fmac_f32_e32 v162, v39, v39
	v_fmac_f32_e32 v162, v40, v40
	v_fmac_f32_e32 v162, v41, v41
	v_fmac_f32_e32 v162, v42, v42
	v_fmac_f32_e32 v162, v43, v43
	v_fmac_f32_e32 v162, v44, v44
	v_fmac_f32_e32 v162, v45, v45
	v_fmac_f32_e32 v162, v46, v46
	v_fmac_f32_e32 v162, v47, v47
	s_waitcnt vmcnt(1)
	v_mul_f32_e32 v163, v48, v48
	v_fmac_f32_e32 v163, v49, v49
	v_fmac_f32_e32 v163, v50, v50
	v_fmac_f32_e32 v163, v51, v51
	v_fmac_f32_e32 v163, v52, v52
	v_fmac_f32_e32 v163, v53, v53
	v_fmac_f32_e32 v163, v54, v54
	v_fmac_f32_e32 v163, v55, v55
	v_fmac_f32_e32 v163, v56, v56
	v_fmac_f32_e32 v163, v57, v57
	v_fmac_f32_e32 v163, v58, v58
	v_fmac_f32_e32 v163, v59, v59
	v_fmac_f32_e32 v163, v60, v60
	v_fmac_f32_e32 v163, v61, v61
	v_fmac_f32_e32 v163, v62, v62
	v_fmac_f32_e32 v163, v63, v63
	s_waitcnt vmcnt(0)
	v_mul_f32_e32 v164, v64, v64
	v_fmac_f32_e32 v164, v65, v65
	v_fmac_f32_e32 v164, v66, v66
	v_fmac_f32_e32 v164, v67, v67
	v_fmac_f32_e32 v164, v68, v68
	v_fmac_f32_e32 v164, v69, v69
	v_fmac_f32_e32 v164, v70, v70
	v_fmac_f32_e32 v164, v71, v71
	v_fmac_f32_e32 v164, v72, v72
	v_fmac_f32_e32 v164, v73, v73
	v_fmac_f32_e32 v164, v74, v74
	v_fmac_f32_e32 v164, v75, v75
	v_fmac_f32_e32 v164, v76, v76
	v_fmac_f32_e32 v164, v77, v77
	v_fmac_f32_e32 v164, v78, v78
	v_fmac_f32_e32 v164, v79, v79
	v_add_f32_dpp v160, v160, v160 quad_perm:[1,0,3,2] row_mask:0xf bank_mask:0xf
	v_add_f32_dpp v161, v161, v161 quad_perm:[1,0,3,2] row_mask:0xf bank_mask:0xf
	v_add_f32_dpp v162, v162, v162 quad_perm:[1,0,3,2] row_mask:0xf bank_mask:0xf
	v_add_f32_dpp v163, v163, v163 quad_perm:[1,0,3,2] row_mask:0xf bank_mask:0xf
	v_add_f32_dpp v164, v164, v164 quad_perm:[1,0,3,2] row_mask:0xf bank_mask:0xf
	v_add_f32_dpp v165, v165, v165 quad_perm:[1,0,3,2] row_mask:0xf bank_mask:0xf
	v_add_f32_dpp v166, v166, v166 quad_perm:[1,0,3,2] row_mask:0xf bank_mask:0xf
	v_add_f32_dpp v167, v167, v167 quad_perm:[1,0,3,2] row_mask:0xf bank_mask:0xf
	v_add_f32_dpp v160, v160, v160 quad_perm:[2,3,0,1] row_mask:0xf bank_mask:0xf
	v_add_f32_dpp v161, v161, v161 quad_perm:[2,3,0,1] row_mask:0xf bank_mask:0xf
	v_add_f32_dpp v162, v162, v162 quad_perm:[2,3,0,1] row_mask:0xf bank_mask:0xf
	v_add_f32_dpp v163, v163, v163 quad_perm:[2,3,0,1] row_mask:0xf bank_mask:0xf
	v_add_f32_dpp v164, v164, v164 quad_perm:[2,3,0,1] row_mask:0xf bank_mask:0xf
	v_add_f32_dpp v165, v165, v165 quad_perm:[2,3,0,1] row_mask:0xf bank_mask:0xf
	v_add_f32_dpp v166, v166, v166 quad_perm:[2,3,0,1] row_mask:0xf bank_mask:0xf
	v_add_f32_dpp v167, v167, v167 quad_perm:[2,3,0,1] row_mask:0xf bank_mask:0xf
	v_add_f32_dpp v160, v160, v160 row_half_mirror row_mask:0xf bank_mask:0xf
	v_add_f32_dpp v161, v161, v161 row_half_mirror row_mask:0xf bank_mask:0xf
	v_add_f32_dpp v162, v162, v162 row_half_mirror row_mask:0xf bank_mask:0xf
	v_add_f32_dpp v163, v163, v163 row_half_mirror row_mask:0xf bank_mask:0xf
	v_add_f32_dpp v164, v164, v164 row_half_mirror row_mask:0xf bank_mask:0xf
	v_add_f32_dpp v165, v165, v165 row_half_mirror row_mask:0xf bank_mask:0xf
	v_add_f32_dpp v166, v166, v166 row_half_mirror row_mask:0xf bank_mask:0xf
	v_add_f32_dpp v167, v167, v167 row_half_mirror row_mask:0xf bank_mask:0xf
	v_add_f32_dpp v160, v160, v160 row_mirror row_mask:0xf bank_mask:0xf
	v_add_f32_dpp v161, v161, v161 row_mirror row_mask:0xf bank_mask:0xf
	v_add_f32_dpp v162, v162, v162 row_mirror row_mask:0xf bank_mask:0xf
	v_add_f32_dpp v163, v163, v163 row_mirror row_mask:0xf bank_mask:0xf
	v_add_f32_dpp v164, v164, v164 row_mirror row_mask:0xf bank_mask:0xf
	v_add_f32_dpp v165, v165, v165 row_mirror row_mask:0xf bank_mask:0xf
	v_add_f32_dpp v166, v166, v166 row_mirror row_mask:0xf bank_mask:0xf
	v_add_f32_dpp v167, v167, v167 row_mirror row_mask:0xf bank_mask:0xf
	v_add_f32_dpp v160, v160, v160 row_bcast:15 row_mask:0xa bank_mask:0xf
	v_add_f32_dpp v161, v161, v161 row_bcast:15 row_mask:0xa bank_mask:0xf
	v_add_f32_dpp v162, v162, v162 row_bcast:15 row_mask:0xa bank_mask:0xf
	v_add_f32_dpp v163, v163, v163 row_bcast:15 row_mask:0xa bank_mask:0xf
	v_add_f32_dpp v164, v164, v164 row_bcast:15 row_mask:0xa bank_mask:0xf
	v_add_f32_dpp v165, v165, v165 row_bcast:15 row_mask:0xa bank_mask:0xf
	v_add_f32_dpp v166, v166, v166 row_bcast:15 row_mask:0xa bank_mask:0xf
	v_add_f32_dpp v167, v167, v167 row_bcast:15 row_mask:0xa bank_mask:0xf
	v_add_f32_dpp v160, v160, v160 row_bcast:31 row_mask:0xc bank_mask:0xf
	v_add_f32_dpp v161, v161, v161 row_bcast:31 row_mask:0xc bank_mask:0xf
	v_add_f32_dpp v162, v162, v162 row_bcast:31 row_mask:0xc bank_mask:0xf
	v_add_f32_dpp v163, v163, v163 row_bcast:31 row_mask:0xc bank_mask:0xf
	v_add_f32_dpp v164, v164, v164 row_bcast:31 row_mask:0xc bank_mask:0xf
	v_add_f32_dpp v165, v165, v165 row_bcast:31 row_mask:0xc bank_mask:0xf
	v_add_f32_dpp v166, v166, v166 row_bcast:31 row_mask:0xc bank_mask:0xf
	v_add_f32_dpp v167, v167, v167 row_bcast:31 row_mask:0xc bank_mask:0xf
	v_fmaak_f32 v160, v160, v174, 0x358637bd
	v_fmaak_f32 v161, v161, v174, 0x358637bd
	v_fmaak_f32 v162, v162, v174, 0x358637bd
	v_fmaak_f32 v163, v163, v174, 0x358637bd
	v_fmaak_f32 v164, v164, v174, 0x358637bd
	v_fmaak_f32 v165, v165, v174, 0x358637bd
	v_fmaak_f32 v166, v166, v174, 0x358637bd
	v_fmaak_f32 v167, v167, v174, 0x358637bd
	v_rsq_f32_e32 v160, v160
	v_rsq_f32_e32 v161, v161
	v_rsq_f32_e32 v162, v162
	v_rsq_f32_e32 v163, v163
	v_rsq_f32_e32 v164, v164
	v_rsq_f32_e32 v165, v165
	v_rsq_f32_e32 v166, v166
	v_rsq_f32_e32 v167, v167
	v_readlane_b32 s84, v160, 63
	v_readlane_b32 s85, v161, 63
	v_readlane_b32 s86, v162, 63
	v_readlane_b32 s87, v163, 63
	v_readlane_b32 s88, v164, 63
	v_readlane_b32 s89, v165, 63
	v_readlane_b32 s90, v166, 63
	v_readlane_b32 s91, v167, 63
	s_waitcnt lgkmcnt(0)
	v_mul_f32_e32 v0, s84, v0
	v_mul_f32_e32 v1, s84, v1
	v_mul_f32_e32 v2, s84, v2
	v_mul_f32_e32 v3, s84, v3
	v_fma_f32 v0, v0, v178, v194
	v_fma_f32 v1, v1, v179, v195
	v_fma_f32 v2, v2, v180, v196
	v_fma_f32 v3, v3, v181, v197
	v_cvt_pk_bf16_f32 v0, v0, v1
	v_cvt_pk_bf16_f32 v1, v2, v3
	global_store_dwordx2 v169, v[0:1], s[10:11] offset:0
	v_mul_f32_e32 v4, s84, v4
	v_mul_f32_e32 v5, s84, v5
	v_mul_f32_e32 v6, s84, v6
	v_mul_f32_e32 v7, s84, v7
	v_fma_f32 v4, v4, v182, v198
	v_fma_f32 v5, v5, v183, v199
	v_fma_f32 v6, v6, v184, v200
	v_fma_f32 v7, v7, v185, v201
	v_cvt_pk_bf16_f32 v4, v4, v5
	v_cvt_pk_bf16_f32 v5, v6, v7
	global_store_dwordx2 v170, v[4:5], s[10:11] offset:0
	v_mul_f32_e32 v8, s84, v8
	v_mul_f32_e32 v9, s84, v9
	v_mul_f32_e32 v10, s84, v10
	v_mul_f32_e32 v11, s84, v11
	v_fma_f32 v8, v8, v186, v202
	v_fma_f32 v9, v9, v187, v203
	v_fma_f32 v10, v10, v188, v204
	v_fma_f32 v11, v11, v189, v205
	v_cvt_pk_bf16_f32 v8, v8, v9
	v_cvt_pk_bf16_f32 v9, v10, v11
	global_store_dwordx2 v171, v[8:9], s[10:11] offset:0
	v_mul_f32_e32 v12, s84, v12
	v_mul_f32_e32 v13, s84, v13
	v_mul_f32_e32 v14, s84, v14
	v_mul_f32_e32 v15, s84, v15
	v_fma_f32 v12, v12, v190, v206
	v_fma_f32 v13, v13, v191, v207
	v_fma_f32 v14, v14, v192, v208
	v_fma_f32 v15, v15, v193, v209
	v_cvt_pk_bf16_f32 v12, v12, v13
	v_cvt_pk_bf16_f32 v13, v14, v15
	global_store_dwordx2 v172, v[12:13], s[10:11] offset:0
	v_mul_f32_e32 v16, s85, v16
	v_mul_f32_e32 v17, s85, v17
	v_mul_f32_e32 v18, s85, v18
	v_mul_f32_e32 v19, s85, v19
	v_fma_f32 v16, v16, v178, v194
	v_fma_f32 v17, v17, v179, v195
	v_fma_f32 v18, v18, v180, v196
	v_fma_f32 v19, v19, v181, v197
	v_cvt_pk_bf16_f32 v16, v16, v17
	v_cvt_pk_bf16_f32 v17, v18, v19
	global_store_dwordx2 v169, v[16:17], s[10:11] offset:16
	v_mul_f32_e32 v20, s85, v20
	v_mul_f32_e32 v21, s85, v21
	v_mul_f32_e32 v22, s85, v22
	v_mul_f32_e32 v23, s85, v23
	v_fma_f32 v20, v20, v182, v198
	v_fma_f32 v21, v21, v183, v199
	v_fma_f32 v22, v22, v184, v200
	v_fma_f32 v23, v23, v185, v201
	v_cvt_pk_bf16_f32 v20, v20, v21
	v_cvt_pk_bf16_f32 v21, v22, v23
	global_store_dwordx2 v170, v[20:21], s[10:11] offset:16
	v_mul_f32_e32 v24, s85, v24
	v_mul_f32_e32 v25, s85, v25
	v_mul_f32_e32 v26, s85, v26
	v_mul_f32_e32 v27, s85, v27
	v_fma_f32 v24, v24, v186, v202
	v_fma_f32 v25, v25, v187, v203
	v_fma_f32 v26, v26, v188, v204
	v_fma_f32 v27, v27, v189, v205
	v_cvt_pk_bf16_f32 v24, v24, v25
	v_cvt_pk_bf16_f32 v25, v26, v27
	global_store_dwordx2 v171, v[24:25], s[10:11] offset:16
	v_mul_f32_e32 v28, s85, v28
	v_mul_f32_e32 v29, s85, v29
	v_mul_f32_e32 v30, s85, v30
	v_mul_f32_e32 v31, s85, v31
	v_fma_f32 v28, v28, v190, v206
	v_fma_f32 v29, v29, v191, v207
	v_fma_f32 v30, v30, v192, v208
	v_fma_f32 v31, v31, v193, v209
	v_cvt_pk_bf16_f32 v28, v28, v29
	v_cvt_pk_bf16_f32 v29, v30, v31
	global_store_dwordx2 v172, v[28:29], s[10:11] offset:16
	v_mul_f32_e32 v32, s86, v32
	v_mul_f32_e32 v33, s86, v33
	v_mul_f32_e32 v34, s86, v34
	v_mul_f32_e32 v35, s86, v35
	v_fma_f32 v32, v32, v178, v194
	v_fma_f32 v33, v33, v179, v195
	v_fma_f32 v34, v34, v180, v196
	v_fma_f32 v35, v35, v181, v197
	v_cvt_pk_bf16_f32 v32, v32, v33
	v_cvt_pk_bf16_f32 v33, v34, v35
	global_store_dwordx2 v169, v[32:33], s[10:11] offset:32
	v_mul_f32_e32 v36, s86, v36
	v_mul_f32_e32 v37, s86, v37
	v_mul_f32_e32 v38, s86, v38
	v_mul_f32_e32 v39, s86, v39
	v_fma_f32 v36, v36, v182, v198
	v_fma_f32 v37, v37, v183, v199
	v_fma_f32 v38, v38, v184, v200
	v_fma_f32 v39, v39, v185, v201
	v_cvt_pk_bf16_f32 v36, v36, v37
	v_cvt_pk_bf16_f32 v37, v38, v39
	global_store_dwordx2 v170, v[36:37], s[10:11] offset:32
	v_mul_f32_e32 v40, s86, v40
	v_mul_f32_e32 v41, s86, v41
	v_mul_f32_e32 v42, s86, v42
	v_mul_f32_e32 v43, s86, v43
	v_fma_f32 v40, v40, v186, v202
	v_fma_f32 v41, v41, v187, v203
	v_fma_f32 v42, v42, v188, v204
	v_fma_f32 v43, v43, v189, v205
	v_cvt_pk_bf16_f32 v40, v40, v41
	v_cvt_pk_bf16_f32 v41, v42, v43
	global_store_dwordx2 v171, v[40:41], s[10:11] offset:32
	v_mul_f32_e32 v44, s86, v44
	v_mul_f32_e32 v45, s86, v45
	v_mul_f32_e32 v46, s86, v46
	v_mul_f32_e32 v47, s86, v47
	v_fma_f32 v44, v44, v190, v206
	v_fma_f32 v45, v45, v191, v207
	v_fma_f32 v46, v46, v192, v208
	v_fma_f32 v47, v47, v193, v209
	v_cvt_pk_bf16_f32 v44, v44, v45
	v_cvt_pk_bf16_f32 v45, v46, v47
	global_store_dwordx2 v172, v[44:45], s[10:11] offset:32
	v_mul_f32_e32 v48, s87, v48
	v_mul_f32_e32 v49, s87, v49
	v_mul_f32_e32 v50, s87, v50
	v_mul_f32_e32 v51, s87, v51
	v_fma_f32 v48, v48, v178, v194
	v_fma_f32 v49, v49, v179, v195
	v_fma_f32 v50, v50, v180, v196
	v_fma_f32 v51, v51, v181, v197
	v_cvt_pk_bf16_f32 v48, v48, v49
	v_cvt_pk_bf16_f32 v49, v50, v51
	global_store_dwordx2 v169, v[48:49], s[10:11] offset:48
	v_mul_f32_e32 v52, s87, v52
	v_mul_f32_e32 v53, s87, v53
	v_mul_f32_e32 v54, s87, v54
	v_mul_f32_e32 v55, s87, v55
	v_fma_f32 v52, v52, v182, v198
	v_fma_f32 v53, v53, v183, v199
	v_fma_f32 v54, v54, v184, v200
	v_fma_f32 v55, v55, v185, v201
	v_cvt_pk_bf16_f32 v52, v52, v53
	v_cvt_pk_bf16_f32 v53, v54, v55
	global_store_dwordx2 v170, v[52:53], s[10:11] offset:48
	v_mul_f32_e32 v56, s87, v56
	v_mul_f32_e32 v57, s87, v57
	v_mul_f32_e32 v58, s87, v58
	v_mul_f32_e32 v59, s87, v59
	v_fma_f32 v56, v56, v186, v202
	v_fma_f32 v57, v57, v187, v203
	v_fma_f32 v58, v58, v188, v204
	v_fma_f32 v59, v59, v189, v205
	v_cvt_pk_bf16_f32 v56, v56, v57
	v_cvt_pk_bf16_f32 v57, v58, v59
	global_store_dwordx2 v171, v[56:57], s[10:11] offset:48
	v_mul_f32_e32 v60, s87, v60
	v_mul_f32_e32 v61, s87, v61
	v_mul_f32_e32 v62, s87, v62
	v_mul_f32_e32 v63, s87, v63
	v_fma_f32 v60, v60, v190, v206
	v_fma_f32 v61, v61, v191, v207
	v_fma_f32 v62, v62, v192, v208
	v_fma_f32 v63, v63, v193, v209
	v_cvt_pk_bf16_f32 v60, v60, v61
	v_cvt_pk_bf16_f32 v61, v62, v63
	global_store_dwordx2 v172, v[60:61], s[10:11] offset:48
	v_mul_f32_e32 v64, s88, v64
	v_mul_f32_e32 v65, s88, v65
	v_mul_f32_e32 v66, s88, v66
	v_mul_f32_e32 v67, s88, v67
	v_fma_f32 v64, v64, v178, v194
	v_fma_f32 v65, v65, v179, v195
	v_fma_f32 v66, v66, v180, v196
	v_fma_f32 v67, v67, v181, v197
	v_cvt_pk_bf16_f32 v64, v64, v65
	v_cvt_pk_bf16_f32 v65, v66, v67
	global_store_dwordx2 v169, v[64:65], s[10:11] offset:64
	v_mul_f32_e32 v68, s88, v68
	v_mul_f32_e32 v69, s88, v69
	v_mul_f32_e32 v70, s88, v70
	v_mul_f32_e32 v71, s88, v71
	v_fma_f32 v68, v68, v182, v198
	v_fma_f32 v69, v69, v183, v199
	v_fma_f32 v70, v70, v184, v200
	v_fma_f32 v71, v71, v185, v201
	v_cvt_pk_bf16_f32 v68, v68, v69
	v_cvt_pk_bf16_f32 v69, v70, v71
	global_store_dwordx2 v170, v[68:69], s[10:11] offset:64
	v_mul_f32_e32 v72, s88, v72
	v_mul_f32_e32 v73, s88, v73
	v_mul_f32_e32 v74, s88, v74
	v_mul_f32_e32 v75, s88, v75
	v_fma_f32 v72, v72, v186, v202
	v_fma_f32 v73, v73, v187, v203
	v_fma_f32 v74, v74, v188, v204
	v_fma_f32 v75, v75, v189, v205
	v_cvt_pk_bf16_f32 v72, v72, v73
	v_cvt_pk_bf16_f32 v73, v74, v75
	global_store_dwordx2 v171, v[72:73], s[10:11] offset:64
	v_mul_f32_e32 v76, s88, v76
	v_mul_f32_e32 v77, s88, v77
	v_mul_f32_e32 v78, s88, v78
	v_mul_f32_e32 v79, s88, v79
	v_fma_f32 v76, v76, v190, v206
	v_fma_f32 v77, v77, v191, v207
	v_fma_f32 v78, v78, v192, v208
	v_fma_f32 v79, v79, v193, v209
	v_cvt_pk_bf16_f32 v76, v76, v77
	v_cvt_pk_bf16_f32 v77, v78, v79
	global_store_dwordx2 v172, v[76:77], s[10:11] offset:64
	v_mul_f32_e32 v80, s89, v80
	v_mul_f32_e32 v81, s89, v81
	v_mul_f32_e32 v82, s89, v82
	v_mul_f32_e32 v83, s89, v83
	v_fma_f32 v80, v80, v178, v194
	v_fma_f32 v81, v81, v179, v195
	v_fma_f32 v82, v82, v180, v196
	v_fma_f32 v83, v83, v181, v197
	v_cvt_pk_bf16_f32 v80, v80, v81
	v_cvt_pk_bf16_f32 v81, v82, v83
	global_store_dwordx2 v169, v[80:81], s[10:11] offset:80
	v_mul_f32_e32 v84, s89, v84
	v_mul_f32_e32 v85, s89, v85
	v_mul_f32_e32 v86, s89, v86
	v_mul_f32_e32 v87, s89, v87
	v_fma_f32 v84, v84, v182, v198
	v_fma_f32 v85, v85, v183, v199
	v_fma_f32 v86, v86, v184, v200
	v_fma_f32 v87, v87, v185, v201
	v_cvt_pk_bf16_f32 v84, v84, v85
	v_cvt_pk_bf16_f32 v85, v86, v87
	global_store_dwordx2 v170, v[84:85], s[10:11] offset:80
	v_mul_f32_e32 v88, s89, v88
	v_mul_f32_e32 v89, s89, v89
	v_mul_f32_e32 v90, s89, v90
	v_mul_f32_e32 v91, s89, v91
	v_fma_f32 v88, v88, v186, v202
	v_fma_f32 v89, v89, v187, v203
	v_fma_f32 v90, v90, v188, v204
	v_fma_f32 v91, v91, v189, v205
	v_cvt_pk_bf16_f32 v88, v88, v89
	v_cvt_pk_bf16_f32 v89, v90, v91
	global_store_dwordx2 v171, v[88:89], s[10:11] offset:80
	v_mul_f32_e32 v92, s89, v92
	v_mul_f32_e32 v93, s89, v93
	v_mul_f32_e32 v94, s89, v94
	v_mul_f32_e32 v95, s89, v95
	v_fma_f32 v92, v92, v190, v206
	v_fma_f32 v93, v93, v191, v207
	v_fma_f32 v94, v94, v192, v208
	v_fma_f32 v95, v95, v193, v209
	v_cvt_pk_bf16_f32 v92, v92, v93
	v_cvt_pk_bf16_f32 v93, v94, v95
	global_store_dwordx2 v172, v[92:93], s[10:11] offset:80
	v_mul_f32_e32 v96, s90, v96
	v_mul_f32_e32 v97, s90, v97
	v_mul_f32_e32 v98, s90, v98
	v_mul_f32_e32 v99, s90, v99
	v_fma_f32 v96, v96, v178, v194
	v_fma_f32 v97, v97, v179, v195
	v_fma_f32 v98, v98, v180, v196
	v_fma_f32 v99, v99, v181, v197
	v_cvt_pk_bf16_f32 v96, v96, v97
	v_cvt_pk_bf16_f32 v97, v98, v99
	global_store_dwordx2 v169, v[96:97], s[10:11] offset:96
	v_mul_f32_e32 v100, s90, v100
	v_mul_f32_e32 v101, s90, v101
	v_mul_f32_e32 v102, s90, v102
	v_mul_f32_e32 v103, s90, v103
	v_fma_f32 v100, v100, v182, v198
	v_fma_f32 v101, v101, v183, v199
	v_fma_f32 v102, v102, v184, v200
	v_fma_f32 v103, v103, v185, v201
	v_cvt_pk_bf16_f32 v100, v100, v101
	v_cvt_pk_bf16_f32 v101, v102, v103
	global_store_dwordx2 v170, v[100:101], s[10:11] offset:96
	v_mul_f32_e32 v104, s90, v104
	v_mul_f32_e32 v105, s90, v105
	v_mul_f32_e32 v106, s90, v106
	v_mul_f32_e32 v107, s90, v107
	v_fma_f32 v104, v104, v186, v202
	v_fma_f32 v105, v105, v187, v203
	v_fma_f32 v106, v106, v188, v204
	v_fma_f32 v107, v107, v189, v205
	v_cvt_pk_bf16_f32 v104, v104, v105
	v_cvt_pk_bf16_f32 v105, v106, v107
	global_store_dwordx2 v171, v[104:105], s[10:11] offset:96
	v_mul_f32_e32 v108, s90, v108
	v_mul_f32_e32 v109, s90, v109
	v_mul_f32_e32 v110, s90, v110
	v_mul_f32_e32 v111, s90, v111
	v_fma_f32 v108, v108, v190, v206
	v_fma_f32 v109, v109, v191, v207
	v_fma_f32 v110, v110, v192, v208
	v_fma_f32 v111, v111, v193, v209
	v_cvt_pk_bf16_f32 v108, v108, v109
	v_cvt_pk_bf16_f32 v109, v110, v111
	global_store_dwordx2 v172, v[108:109], s[10:11] offset:96
	v_mul_f32_e32 v112, s91, v112
	v_mul_f32_e32 v113, s91, v113
	v_mul_f32_e32 v114, s91, v114
	v_mul_f32_e32 v115, s91, v115
	v_fma_f32 v112, v112, v178, v194
	v_fma_f32 v113, v113, v179, v195
	v_fma_f32 v114, v114, v180, v196
	v_fma_f32 v115, v115, v181, v197
	v_cvt_pk_bf16_f32 v112, v112, v113
	v_cvt_pk_bf16_f32 v113, v114, v115
	global_store_dwordx2 v169, v[112:113], s[10:11] offset:112
	v_mul_f32_e32 v116, s91, v116
	v_mul_f32_e32 v117, s91, v117
	v_mul_f32_e32 v118, s91, v118
	v_mul_f32_e32 v119, s91, v119
	v_fma_f32 v116, v116, v182, v198
	v_fma_f32 v117, v117, v183, v199
	v_fma_f32 v118, v118, v184, v200
	v_fma_f32 v119, v119, v185, v201
	v_cvt_pk_bf16_f32 v116, v116, v117
	v_cvt_pk_bf16_f32 v117, v118, v119
	global_store_dwordx2 v170, v[116:117], s[10:11] offset:112
	v_mul_f32_e32 v120, s91, v120
	v_mul_f32_e32 v121, s91, v121
	v_mul_f32_e32 v122, s91, v122
	v_mul_f32_e32 v123, s91, v123
	v_fma_f32 v120, v120, v186, v202
	v_fma_f32 v121, v121, v187, v203
	v_fma_f32 v122, v122, v188, v204
	v_fma_f32 v123, v123, v189, v205
	v_cvt_pk_bf16_f32 v120, v120, v121
	v_cvt_pk_bf16_f32 v121, v122, v123
	global_store_dwordx2 v171, v[120:121], s[10:11] offset:112
	v_mul_f32_e32 v124, s91, v124
	v_mul_f32_e32 v125, s91, v125
	v_mul_f32_e32 v126, s91, v126
	v_mul_f32_e32 v127, s91, v127
	v_fma_f32 v124, v124, v190, v206
	v_fma_f32 v125, v125, v191, v207
	v_fma_f32 v126, v126, v192, v208
	v_fma_f32 v127, v127, v193, v209
	v_cvt_pk_bf16_f32 v124, v124, v125
	v_cvt_pk_bf16_f32 v125, v126, v127
	global_store_dwordx2 v172, v[124:125], s[10:11] offset:112
	s_add_i32 s4, s4, s3
	s_cmpk_lt_i32 s4, 0x200
	s_cbranch_scc1 .Lmy_hdn1_loop
